# A2 loop back edge rotated (in-place running sums, single conditional back branch, dead pointer advance removed); D: in-place init-tuple update skipped when unchanged
# speedup vs baseline: 1.0010x; 1.0010x over previous
; #define SBAR() __builtin_amdgcn_sched_barrier(0)
; #define SLOAD2(k0) do { vs0 = *reinterpret_cast<const bf16x8*>(&Vh[(long)((k0) + sr) * ldv + sc]); vs1 = *reinterpret_cast<const bf16x8*>(&Vh[(long)((k0) + 32 + sr) * ldv + sc]); \
;     ks0 = *reinterpret_cast<const bf16x8*>(&Kh[(long)((k0) + sr) * ldk + sc]); ks1 = *reinterpret_cast<const bf16x8*>(&Kh[(long)((k0) + 32 + sr) * ldk + sc]); } while (0)
; #define SWRITE2(b) do { *(bf16x8*)(V_lds + (b) * SHM_V + vst0) = vs0; *(bf16x8*)(V_lds + (b) * SHM_V + vst1) = vs1; \
;     *(bf16x8*)(K_lds + (b) * SHM_K + KSWZ(sr, sc * 2)) = ks0; *(bf16x8*)(K_lds + (b) * SHM_K + KSWZ(32 + sr, sc * 2)) = ks1; } while (0)
; #define RESC2(O, SL, a) do { if (__any((a) < 1.f)) { if (hi == 0) SL[r32] = (a); asm volatile("s_waitcnt lgkmcnt(0)" ::: "memory"); \
;     _Pragma("unroll") for (int d = 0; d < 4; ++d) _Pragma("unroll") for (int r = 0; r < 16; ++r) O[d][r] *= SL[crow(r, hi)]; } } while (0)
; __device__ __forceinline__ void softmax_tile(f32x16& p0, f32x16& p1, float& m, float& l, float& alpha, float cb, bf16x8& pa0, bf16x8& pa1, bf16x8& pa2, bf16x8& pa3) {
;     ...
;   { auto rr = __builtin_amdgcn_permlane32_swap(__float_as_uint(ps), __float_as_uint(ps), false, false);
;     ps = __uint_as_float(rr[0]) + __uint_as_float(rr[1]); }
;   l = l * alpha + ps;
; __device__ __forceinline__ void attn_unit_A2(const bf16_t* __restrict__ Qb, int ldq, const bf16_t* __restrict__ Kh, int ldk, const bf16_t* __restrict__ Vh, int ldv, int nkeys, int q0, ...
;     ...
;     SBAR();
;     softmax_tile(s0, s1, m1, l1, al1, cb, pa0, pa1, pa2, pa3);
;     RESC2(ob, sl1, al1);
;     SBAR();
;     if (j + 1 < NT) SLOAD2(kt0 + KVBLK);
;     SBAR();
;     pv_d0(ob, vb, pa0, pa1, pa2, pa3);
;     if (j + 1 < NT) { asm volatile("s_waitcnt vmcnt(0)" ::: "memory"); SWRITE2(b ^ 1); }
;     __syncthreads();
;   }
.LBB0_351:
	v_add_f32_e32 v2, v148, v149
	v_add_f32_e32 v3, v220, v221
	s_addk_i32 s63, 0x100
	s_addk_i32 s62, 0x4000
	s_add_i32 s11, s11, 64
	v_fma_f32 v219, v219, v223, v2
	v_fma_f32 v14, v14, v15, v3
	s_cmp_eq_u32 s63, 0x10000
	s_waitcnt lgkmcnt(0)
	s_barrier
	s_cbranch_scc0 .LBB0_335
	v_mov_b32_e32 v2, v219
	v_mov_b32_e32 v3, v14
	s_branch .LBB0_353
